# SwiGLU and Win unit headers: group size 8 takes a shift instead of the generic reciprocal division
# baseline (speedup 1.0000x reference)
.LBB0_249:
	s_add_i32 s58, s58, 1
	s_mul_i32 s4, s58, s57
	s_mul_hi_u32 s5, s58, s26
	s_add_i32 s5, s5, s4
	s_mul_i32 s4, s58, s26
	s_add_u32 s14, s4, s27
	s_addc_u32 s15, s5, s43
	v_mov_b64_e32 v[0:1], s[44:45]
	v_cmp_ge_i64_e32 vcc, s[14:15], v[0:1]
	v_cmp_lt_i64_e64 s[4:5], s[14:15], v[0:1]
	s_cbranch_vccnz .LBB0_251
	s_ashr_i32 s10, s14, 31
	s_lshr_b32 s10, s10, 29
	s_add_i32 s10, s14, s10
	s_ashr_i32 s11, s10, 3
	s_and_b32 s10, s10, -8
	s_sub_i32 s10, s14, s10
	s_cmp_lt_i32 s10, 0
	s_cselect_b32 s12, s48, s42
	s_mul_i32 s10, s12, s10
	s_add_i32 s10, s10, s11
	s_mul_hi_i32 s11, s10, 0x2e8ba2e9
	s_lshr_b32 s12, s11, 31
	s_ashr_i32 s11, s11, 5
	s_add_i32 s11, s11, s12
	s_lshl_b32 s12, s11, 3
	s_sub_i32 s13, s28, s12
	s_min_i32 s13, s13, 8
	s_cmp_lg_u32 s13, 8
	s_cbranch_scc1 .Ldiv_slow_sw
	s_mulk_i32 s11, 0xb0
	s_sub_i32 s11, s10, s11
	s_lshr_b32 s10, s11, 3
	s_branch .Ldiv_join_sw
.Ldiv_slow_sw:
	s_abs_i32 s14, s13
	v_cvt_f32_u32_e32 v0, s14
	s_sub_i32 s16, 0, s14
	s_mulk_i32 s11, 0xb0
	s_sub_i32 s11, s10, s11
	v_rcp_iflag_f32_e32 v0, v0
	s_abs_i32 s10, s11
	s_xor_b32 s15, s11, s13
	s_ashr_i32 s15, s15, 31
	v_mul_f32_e32 v0, 0x4f7ffffe, v0
	v_cvt_u32_f32_e32 v0, v0
	s_nop 0
	v_readfirstlane_b32 s17, v0
	s_mul_i32 s16, s16, s17
	s_mul_hi_u32 s16, s17, s16
	s_add_i32 s17, s17, s16
	s_mul_hi_u32 s16, s10, s17
	s_mul_i32 s17, s16, s14
	s_sub_i32 s10, s10, s17
	s_add_i32 s19, s16, 1
	s_sub_i32 s17, s10, s14
	s_cmp_ge_u32 s10, s14
	s_cselect_b32 s16, s19, s16
	s_cselect_b32 s10, s17, s10
	s_add_i32 s17, s16, 1
	s_cmp_ge_u32 s10, s14
	s_cselect_b32 s10, s17, s16
	s_xor_b32 s10, s10, s15
	s_sub_i32 s10, s10, s15
.Ldiv_join_sw:
	s_mul_i32 s13, s10, s13
	s_sub_i32 s11, s11, s13
	s_add_i32 s12, s11, s12

.LBB0_631:
	s_add_i32 s59, s59, 1
	s_mul_i32 s4, s59, s58
	s_mul_hi_u32 s5, s59, s26
	s_add_i32 s5, s5, s4
	s_mul_i32 s4, s59, s26
	s_add_u32 s14, s4, s27
	s_addc_u32 s15, s5, s48
	v_mov_b64_e32 v[0:1], s[0:1]
	v_cmp_ge_i64_e32 vcc, s[14:15], v[0:1]
	v_cmp_lt_i64_e64 s[4:5], s[14:15], v[0:1]
	s_cbranch_vccnz .LBB0_633
	s_ashr_i32 s10, s14, 31
	s_lshr_b32 s10, s10, 29
	s_add_i32 s10, s14, s10
	s_ashr_i32 s11, s10, 3
	s_and_b32 s10, s10, -8
	s_sub_i32 s10, s14, s10
	s_cmp_lt_i32 s10, 0
	s_cselect_b32 s12, s49, s47
	s_mul_i32 s10, s12, s10
	s_add_i32 s10, s10, s11
	s_mul_hi_i32 s11, s10, 0x2aaaaaab
	s_lshr_b32 s12, s11, 31
	s_ashr_i32 s11, s11, 4
	s_add_i32 s11, s11, s12
	s_lshl_b32 s12, s11, 3
	s_sub_i32 s13, s28, s12
	s_min_i32 s13, s13, 8
	s_cmp_lg_u32 s13, 8
	s_cbranch_scc1 .Ldiv_slow_win
	s_mulk_i32 s11, 0x60
	s_sub_i32 s11, s10, s11
	s_lshr_b32 s10, s11, 3
	s_branch .Ldiv_join_win
.Ldiv_slow_win:
	s_abs_i32 s14, s13
	v_cvt_f32_u32_e32 v0, s14
	s_sub_i32 s16, 0, s14
	s_mulk_i32 s11, 0x60
	s_sub_i32 s11, s10, s11
	v_rcp_iflag_f32_e32 v0, v0
	s_abs_i32 s10, s11
	s_xor_b32 s15, s11, s13
	s_ashr_i32 s15, s15, 31
	v_mul_f32_e32 v0, 0x4f7ffffe, v0
	v_cvt_u32_f32_e32 v0, v0
	s_nop 0
	v_readfirstlane_b32 s17, v0
	s_mul_i32 s16, s16, s17
	s_mul_hi_u32 s16, s17, s16
	s_add_i32 s17, s17, s16
	s_mul_hi_u32 s16, s10, s17
	s_mul_i32 s17, s16, s14
	s_sub_i32 s10, s10, s17
	s_add_i32 s19, s16, 1
	s_sub_i32 s17, s10, s14
	s_cmp_ge_u32 s10, s14
	s_cselect_b32 s16, s19, s16
	s_cselect_b32 s10, s17, s10
	s_add_i32 s17, s16, 1
	s_cmp_ge_u32 s10, s14
	s_cselect_b32 s10, s17, s16
	s_xor_b32 s10, s10, s15
	s_sub_i32 s10, s10, s15
